# v12 plus layer 0's lora-up GEMM skipping plane 3 (v-residual gate, never read when there is no previous layer): 12 instead of 16 column tiles
# speedup vs baseline: 1.0092x; 1.0007x over previous
.LBB0_251:
	v_readlane_b32 s46, v254, 63
	v_readlane_b32 s94, v255, 1
	v_readlane_b32 s30, v255, 3
	s_mov_b64 s[14:15], 0x400
	s_mov_b32 s16, 3
	v_readlane_b32 s24, v254, 22
	s_cmp_eq_u32 s24, 0
	s_cselect_b32 s24, 12, 16
	s_mov_b32 s72, 0
	s_movk_i32 s48, 0x180
	s_mov_b64 s[34:35], -1
	s_mov_b64 s[40:41], 0
	s_mov_b64 s[56:57], 0
	s_mov_b64 s[68:69], 0
	s_mov_b64 s[6:7], 0
	v_readlane_b32 s47, v255, 0
	v_readlane_b32 s95, v255, 2
	s_movk_i32 s49, 0x180
	s_movk_i32 s54, 0x180
	v_readlane_b32 s31, v255, 4
